# store-drain vmcnt waits at item-loop heads (conv_ssd, conv_hy, hy_final, hy_lat, hy_ctx) replaced by no-ops so stores overlap next item loads
# baseline (speedup 1.0000x reference)
.LBB0_384:
	s_lshl_b32 s20, s23, 6
	s_nop 0
	v_mbcnt_lo_u32_b32 v0, -1, 0
	v_mbcnt_hi_u32_b32 v0, -1, v0
	s_ashr_i32 s21, s20, 31
	v_add_u32_e32 v0, s95, v0
	s_lshl_b64 s[0:1], s[20:21], 1
	s_add_u32 s0, s18, s0
	v_lshlrev_b32_e32 v1, 4, v0
	s_addc_u32 s1, s19, s1
	v_and_b32_e32 v176, 0x70, v1
	s_nop 0
	v_lshl_add_u64 v[6:7], s[0:1], 0, v[176:177]
	v_ashrrev_i32_e32 v1, 3, v0
	s_mov_b32 s3, 0x22000
	v_mad_i64_i32 v[2:3], s[0:1], v1, s3, v[6:7]
	s_barrier
	v_add_u32_e32 v8, s52, v176
	s_movk_i32 s2, 0x84
	v_mad_u64_u32 v[10:11], s[0:1], v1, s2, v[8:9]
	v_and_b32_e32 v30, 63, v0
	s_mov_b64 s[0:1], 0x440000
	global_load_dwordx4 v[32:35], v[2:3], off
	v_lshl_add_u64 v[2:3], v[2:3], 0, s[0:1]
	global_load_dwordx4 v[36:39], v[2:3], off
	v_lshl_add_u64 v[2:3], v[2:3], 0, s[0:1]
	global_load_dwordx4 v[40:43], v[2:3], off
	v_lshl_add_u64 v[2:3], v[2:3], 0, s[0:1]
	global_load_dwordx4 v[44:47], v[2:3], off
	v_lshl_add_u64 v[2:3], v[2:3], 0, s[0:1]
	global_load_dwordx4 v[48:51], v[2:3], off
	v_lshl_add_u64 v[2:3], v[2:3], 0, s[0:1]
	global_load_dwordx4 v[52:55], v[2:3], off
	v_lshl_add_u64 v[2:3], v[2:3], 0, s[0:1]
	global_load_dwordx4 v[56:59], v[2:3], off
	v_lshl_add_u64 v[2:3], v[2:3], 0, s[0:1]
	global_load_dwordx4 v[60:63], v[2:3], off
	s_waitcnt vmcnt(7)
	ds_write2_b32 v10, v32, v33 offset1:1
	ds_write2_b32 v10, v34, v35 offset0:2 offset1:3
	s_waitcnt vmcnt(6)
	v_add_u32_e32 v11, 4224, v10
	ds_write2_b32 v11, v36, v37 offset1:1
	ds_write2_b32 v11, v38, v39 offset0:2 offset1:3
	s_waitcnt vmcnt(5)
	v_add_u32_e32 v11, 8448, v10
	ds_write2_b32 v11, v40, v41 offset1:1
	ds_write2_b32 v11, v42, v43 offset0:2 offset1:3
	s_waitcnt vmcnt(4)
	v_add_u32_e32 v11, 12672, v10
	ds_write2_b32 v11, v44, v45 offset1:1
	ds_write2_b32 v11, v46, v47 offset0:2 offset1:3
	s_waitcnt vmcnt(3)
	v_add_u32_e32 v11, 16896, v10
	ds_write2_b32 v11, v48, v49 offset1:1
	ds_write2_b32 v11, v50, v51 offset0:2 offset1:3
	s_waitcnt vmcnt(2)
	v_add_u32_e32 v11, 21120, v10
	ds_write2_b32 v11, v52, v53 offset1:1
	ds_write2_b32 v11, v54, v55 offset0:2 offset1:3
	s_waitcnt vmcnt(1)
	v_add_u32_e32 v11, 25344, v10
	ds_write2_b32 v11, v56, v57 offset1:1
	ds_write2_b32 v11, v58, v59 offset0:2 offset1:3
	s_waitcnt vmcnt(0)
	v_add_u32_e32 v11, 29568, v10
	ds_write2_b32 v11, v60, v61 offset1:1
	ds_write2_b32 v11, v62, v63 offset0:2 offset1:3
	s_movk_i32 s0, 0x2100
	v_or_b32_e32 v1, 63, v0
	s_mov_b64 s[2:3], 0
	v_lshrrev_b32_e32 v3, 6, v0
	v_mul_lo_u32 v3, v3, s0
	v_and_b32_e32 v2, 0xffffffc0, v0
	v_lshl_or_b32 v3, v30, 1, v3
	v_add_u32_e32 v2, -1, v2
	v_add_u32_e32 v4, s52, v3
	v_mov_b32_e32 v3, 0
	s_waitcnt lgkmcnt(0)
	s_barrier

.LBB0_393:
	s_cmp_ge_i32 s13, s12
	s_mov_b64 s[2:3], -1
	s_cbranch_scc0 .LBB0_420
	s_sub_i32 s0, s13, s12
	s_lshr_b32 s10, s0, 2
	v_readlane_b32 s0, v245, 47
	v_readlane_b32 s1, v245, 48
	s_add_i32 s0, s10, 0x100
	v_writelane_b32 v245, s0, 47
	s_nop 0
	v_mbcnt_lo_u32_b32 v0, -1, 0
	v_mbcnt_hi_u32_b32 v0, -1, v0
	s_nop 0
	v_add_u32_e32 v1, s95, v0
	v_writelane_b32 v245, s1, 48
	s_movk_i32 s0, 0x2000
	s_nop 0
	v_cmp_gt_i32_e32 vcc, s0, v1
	s_barrier
	s_and_saveexec_b64 s[2:3], vcc
	s_cbranch_execz .LBB0_401
	v_readlane_b32 s0, v245, 47
	v_readlane_b32 s1, v245, 48
	v_readlane_b32 s20, v245, 51
	s_lshl_b64 s[0:1], s[0:1], 15
	v_readlane_b32 s22, v245, 53
	v_readlane_b32 s23, v245, 54
	s_add_u32 s4, s22, s0
	s_addc_u32 s5, s23, s1
	v_sub_u32_e32 v176, 0x2000, v1
	v_lshl_add_u32 v0, v1, 1, s52
	s_mov_b64 s[6:7], 0
	v_mov_b32_e32 v2, v1
	v_readlane_b32 s21, v245, 52
	v_readlane_b32 s24, v245, 55
	v_readlane_b32 s25, v245, 56
	v_readlane_b32 s26, v245, 57
	v_readlane_b32 s27, v245, 58
	v_lshlrev_b32_e32 v4, 2, v176
	v_mov_b32_e32 v6, 0
	v_cmp_ne_u32_e32 vcc, 0, v1
	s_mov_b64 s[6:7], s[4:5]
	s_and_saveexec_b64 s[8:9], vcc
	global_load_dword v6, v4, s[6:7]
	s_or_b64 exec, exec, s[8:9]
	global_load_dword v7, v4, s[6:7] offset:-1024
	global_load_dword v8, v4, s[6:7] offset:-2048
	global_load_dword v9, v4, s[6:7] offset:-3072
	s_sub_u32 s6, s6, 0x1000
	s_subb_u32 s7, s7, 0
	global_load_dword v10, v4, s[6:7]
	global_load_dword v11, v4, s[6:7] offset:-1024
	global_load_dword v12, v4, s[6:7] offset:-2048
	global_load_dword v13, v4, s[6:7] offset:-3072
	s_sub_u32 s6, s6, 0x1000
	s_subb_u32 s7, s7, 0
	global_load_dword v14, v4, s[6:7]
	global_load_dword v15, v4, s[6:7] offset:-1024
	global_load_dword v16, v4, s[6:7] offset:-2048
	global_load_dword v17, v4, s[6:7] offset:-3072
	s_sub_u32 s6, s6, 0x1000
	s_subb_u32 s7, s7, 0
	global_load_dword v18, v4, s[6:7]
	global_load_dword v19, v4, s[6:7] offset:-1024
	global_load_dword v20, v4, s[6:7] offset:-2048
	global_load_dword v21, v4, s[6:7] offset:-3072
	s_sub_u32 s6, s6, 0x1000
	s_subb_u32 s7, s7, 0
	global_load_dword v22, v4, s[6:7]
	global_load_dword v23, v4, s[6:7] offset:-1024
	global_load_dword v24, v4, s[6:7] offset:-2048
	global_load_dword v25, v4, s[6:7] offset:-3072
	s_sub_u32 s6, s6, 0x1000
	s_subb_u32 s7, s7, 0
	global_load_dword v26, v4, s[6:7]
	global_load_dword v27, v4, s[6:7] offset:-1024
	global_load_dword v28, v4, s[6:7] offset:-2048
	global_load_dword v29, v4, s[6:7] offset:-3072
	s_sub_u32 s6, s6, 0x1000
	s_subb_u32 s7, s7, 0
	global_load_dword v30, v4, s[6:7]
	global_load_dword v31, v4, s[6:7] offset:-1024
	global_load_dword v32, v4, s[6:7] offset:-2048
	global_load_dword v33, v4, s[6:7] offset:-3072
	s_sub_u32 s6, s6, 0x1000
	s_subb_u32 s7, s7, 0
	global_load_dword v34, v4, s[6:7]
	global_load_dword v35, v4, s[6:7] offset:-1024
	global_load_dword v36, v4, s[6:7] offset:-2048
	global_load_dword v37, v4, s[6:7] offset:-3072
	s_waitcnt vmcnt(31)
	v_cvt_pk_bf16_f32 v6, v6, v6
	ds_write_b16 v0, v6
	v_cmp_lt_i32_e32 vcc, 0, v1
	s_and_saveexec_b64 s[8:9], vcc
	ds_write_b16 v0, v6 offset:16446
	s_or_b64 exec, exec, s[8:9]
	s_waitcnt vmcnt(30)
	v_cvt_pk_bf16_f32 v7, v7, v7
	ds_write_b16 v0, v7 offset:512
	ds_write_b16 v0, v7 offset:16958
	s_waitcnt vmcnt(29)
	v_cvt_pk_bf16_f32 v8, v8, v8
	ds_write_b16 v0, v8 offset:1024
	ds_write_b16 v0, v8 offset:17470
	s_waitcnt vmcnt(28)
	v_cvt_pk_bf16_f32 v9, v9, v9
	ds_write_b16 v0, v9 offset:1536
	ds_write_b16 v0, v9 offset:17982
	s_waitcnt vmcnt(27)
	v_cvt_pk_bf16_f32 v10, v10, v10
	ds_write_b16 v0, v10 offset:2048
	ds_write_b16 v0, v10 offset:18494
	s_waitcnt vmcnt(26)
	v_cvt_pk_bf16_f32 v11, v11, v11
	ds_write_b16 v0, v11 offset:2560
	ds_write_b16 v0, v11 offset:19006
	s_waitcnt vmcnt(25)
	v_cvt_pk_bf16_f32 v12, v12, v12
	ds_write_b16 v0, v12 offset:3072
	ds_write_b16 v0, v12 offset:19518
	s_waitcnt vmcnt(24)
	v_cvt_pk_bf16_f32 v13, v13, v13
	ds_write_b16 v0, v13 offset:3584
	ds_write_b16 v0, v13 offset:20030
	s_waitcnt vmcnt(23)
	v_cvt_pk_bf16_f32 v14, v14, v14
	ds_write_b16 v0, v14 offset:4096
	ds_write_b16 v0, v14 offset:20542
	s_waitcnt vmcnt(22)
	v_cvt_pk_bf16_f32 v15, v15, v15
	ds_write_b16 v0, v15 offset:4608
	ds_write_b16 v0, v15 offset:21054
	s_waitcnt vmcnt(21)
	v_cvt_pk_bf16_f32 v16, v16, v16
	ds_write_b16 v0, v16 offset:5120
	ds_write_b16 v0, v16 offset:21566
	s_waitcnt vmcnt(20)
	v_cvt_pk_bf16_f32 v17, v17, v17
	ds_write_b16 v0, v17 offset:5632
	ds_write_b16 v0, v17 offset:22078
	s_waitcnt vmcnt(19)
	v_cvt_pk_bf16_f32 v18, v18, v18
	ds_write_b16 v0, v18 offset:6144
	ds_write_b16 v0, v18 offset:22590
	s_waitcnt vmcnt(18)
	v_cvt_pk_bf16_f32 v19, v19, v19
	ds_write_b16 v0, v19 offset:6656
	ds_write_b16 v0, v19 offset:23102
	s_waitcnt vmcnt(17)
	v_cvt_pk_bf16_f32 v20, v20, v20
	ds_write_b16 v0, v20 offset:7168
	ds_write_b16 v0, v20 offset:23614
	s_waitcnt vmcnt(16)
	v_cvt_pk_bf16_f32 v21, v21, v21
	ds_write_b16 v0, v21 offset:7680
	ds_write_b16 v0, v21 offset:24126
	s_waitcnt vmcnt(15)
	v_cvt_pk_bf16_f32 v22, v22, v22
	ds_write_b16 v0, v22 offset:8192
	ds_write_b16 v0, v22 offset:24638
	s_waitcnt vmcnt(14)
	v_cvt_pk_bf16_f32 v23, v23, v23
	ds_write_b16 v0, v23 offset:8704
	ds_write_b16 v0, v23 offset:25150
	s_waitcnt vmcnt(13)
	v_cvt_pk_bf16_f32 v24, v24, v24
	ds_write_b16 v0, v24 offset:9216
	ds_write_b16 v0, v24 offset:25662
	s_waitcnt vmcnt(12)
	v_cvt_pk_bf16_f32 v25, v25, v25
	ds_write_b16 v0, v25 offset:9728
	ds_write_b16 v0, v25 offset:26174
	s_waitcnt vmcnt(11)
	v_cvt_pk_bf16_f32 v26, v26, v26
	ds_write_b16 v0, v26 offset:10240
	ds_write_b16 v0, v26 offset:26686
	s_waitcnt vmcnt(10)
	v_cvt_pk_bf16_f32 v27, v27, v27
	ds_write_b16 v0, v27 offset:10752
	ds_write_b16 v0, v27 offset:27198
	s_waitcnt vmcnt(9)
	v_cvt_pk_bf16_f32 v28, v28, v28
	ds_write_b16 v0, v28 offset:11264
	ds_write_b16 v0, v28 offset:27710
	s_waitcnt vmcnt(8)
	v_cvt_pk_bf16_f32 v29, v29, v29
	ds_write_b16 v0, v29 offset:11776
	ds_write_b16 v0, v29 offset:28222
	s_waitcnt vmcnt(7)
	v_cvt_pk_bf16_f32 v30, v30, v30
	ds_write_b16 v0, v30 offset:12288
	ds_write_b16 v0, v30 offset:28734
	s_waitcnt vmcnt(6)
	v_cvt_pk_bf16_f32 v31, v31, v31
	ds_write_b16 v0, v31 offset:12800
	ds_write_b16 v0, v31 offset:29246
	s_waitcnt vmcnt(5)
	v_cvt_pk_bf16_f32 v32, v32, v32
	ds_write_b16 v0, v32 offset:13312
	ds_write_b16 v0, v32 offset:29758
	s_waitcnt vmcnt(4)
	v_cvt_pk_bf16_f32 v33, v33, v33
	ds_write_b16 v0, v33 offset:13824
	ds_write_b16 v0, v33 offset:30270
	s_waitcnt vmcnt(3)
	v_cvt_pk_bf16_f32 v34, v34, v34
	ds_write_b16 v0, v34 offset:14336
	ds_write_b16 v0, v34 offset:30782
	s_waitcnt vmcnt(2)
	v_cvt_pk_bf16_f32 v35, v35, v35
	ds_write_b16 v0, v35 offset:14848
	ds_write_b16 v0, v35 offset:31294
	s_waitcnt vmcnt(1)
	v_cvt_pk_bf16_f32 v36, v36, v36
	ds_write_b16 v0, v36 offset:15360
	ds_write_b16 v0, v36 offset:31806
	s_waitcnt vmcnt(0)
	v_cvt_pk_bf16_f32 v37, v37, v37
	ds_write_b16 v0, v37 offset:15872
	ds_write_b16 v0, v37 offset:32318

.LBB0_420:
	s_and_b64 vcc, exec, s[2:3]
	s_cbranch_vccz .LBB0_392
	s_nop 0
	v_mbcnt_lo_u32_b32 v0, -1, 0
	v_mbcnt_hi_u32_b32 v0, -1, v0
	s_ashr_i32 s0, s13, 1
	v_add_u32_e32 v10, s95, v0
	s_movk_i32 s1, 0x200
	s_add_i32 s4, s0, 0x100
	v_cmp_gt_i32_e32 vcc, s1, v10
	s_barrier
	s_and_saveexec_b64 s[2:3], vcc
	s_cbranch_execz .LBB0_426
	s_ashr_i32 s5, s4, 31
	v_readlane_b32 s20, v245, 51
	s_lshl_b64 s[6:7], s[4:5], 11
	v_readlane_b32 s24, v245, 55
	v_readlane_b32 s25, v245, 56
	s_add_u32 s6, s24, s6
	s_addc_u32 s7, s25, s7
	v_lshl_add_u32 v0, v10, 2, s52
	s_mov_b64 s[8:9], 0
	v_mov_b32_e32 v176, v10
	v_readlane_b32 s21, v245, 52
	v_readlane_b32 s22, v245, 53
	v_readlane_b32 s23, v245, 54
	v_readlane_b32 s26, v245, 57
	v_readlane_b32 s27, v245, 58
	s_branch .LBB0_424

.LBB0_434:
	s_or_b64 exec, exec, s[2:3]
	v_lshlrev_b32_e32 v0, 3, v10
	v_and_b32_e32 v9, 0xf8, v0
	v_lshl_add_u32 v8, v9, 2, s52
	s_waitcnt lgkmcnt(0)
	s_barrier
	ds_read_b128 v[0:3], v8 offset:1024
	s_nop 0
	ds_read_b128 v[4:7], v8 offset:1040
	v_ashrrev_i32_e32 v24, 5, v10
	v_mul_lo_u32 v11, v24, s10
	v_readlane_b32 s2, v246, 45
	v_and_b32_e32 v10, 31, v10
	v_mov_b32_e32 v12, 0
	v_add_u32_e32 v26, s2, v11
	v_readlane_b32 s2, v246, 46
	v_add_u32_e32 v25, 0x400, v8
	s_movk_i32 s5, 0x404
	v_lshl_add_u32 v27, v10, 5, s2
	s_mov_b32 s2, 0
	v_mov_b32_e32 v13, v12
	v_mov_b32_e32 v14, v12
	v_mov_b32_e32 v15, v12
	v_mov_b32_e32 v16, v12
	v_mov_b32_e32 v17, v12
	v_mov_b32_e32 v18, v12
	v_mov_b32_e32 v19, v12

.LBB0_463:
	s_cmp_ge_i32 s13, s12
	s_mov_b64 s[2:3], -1
	s_cbranch_scc0 .LBB0_490
	s_sub_i32 s0, s13, s12
	v_readlane_b32 s2, v245, 47
	s_nop 0
	v_mbcnt_lo_u32_b32 v0, -1, 0
	v_mbcnt_hi_u32_b32 v0, -1, v0
	v_readlane_b32 s3, v245, 48
	v_add_u32_e32 v1, s95, v0
	s_lshr_b32 s2, s0, 2
	s_movk_i32 s0, 0x2000
	v_writelane_b32 v245, s2, 47
	v_cmp_gt_i32_e32 vcc, s0, v1
	s_waitcnt lgkmcnt(0)
	v_writelane_b32 v245, s3, 48
	s_barrier
	s_and_saveexec_b64 s[2:3], vcc
	s_cbranch_execz .LBB0_471
	v_readlane_b32 s0, v245, 47
	v_readlane_b32 s1, v245, 48
	v_readlane_b32 s4, v245, 51
	s_lshl_b64 s[0:1], s[0:1], 15
	v_readlane_b32 s6, v245, 53
	v_readlane_b32 s5, v245, 52
	v_readlane_b32 s7, v245, 54
	s_add_u32 s4, s6, s0
	s_addc_u32 s5, s7, s1
	v_sub_u32_e32 v176, 0x2000, v1
	v_lshl_add_u32 v0, v1, 1, s52
	s_mov_b64 s[6:7], 0
	v_mov_b32_e32 v2, v1
	v_readlane_b32 s8, v245, 55
	v_readlane_b32 s9, v245, 56
	v_readlane_b32 s10, v245, 57
	v_readlane_b32 s11, v245, 58
	v_lshlrev_b32_e32 v4, 2, v176
	v_mov_b32_e32 v6, 0
	v_cmp_ne_u32_e32 vcc, 0, v1
	s_mov_b64 s[6:7], s[4:5]
	s_and_saveexec_b64 s[8:9], vcc
	global_load_dword v6, v4, s[6:7]
	s_or_b64 exec, exec, s[8:9]
	global_load_dword v7, v4, s[6:7] offset:-1024
	global_load_dword v8, v4, s[6:7] offset:-2048
	global_load_dword v9, v4, s[6:7] offset:-3072
	s_sub_u32 s6, s6, 0x1000
	s_subb_u32 s7, s7, 0
	global_load_dword v10, v4, s[6:7]
	global_load_dword v11, v4, s[6:7] offset:-1024
	global_load_dword v12, v4, s[6:7] offset:-2048
	global_load_dword v13, v4, s[6:7] offset:-3072
	s_sub_u32 s6, s6, 0x1000
	s_subb_u32 s7, s7, 0
	global_load_dword v14, v4, s[6:7]
	global_load_dword v15, v4, s[6:7] offset:-1024
	global_load_dword v16, v4, s[6:7] offset:-2048
	global_load_dword v17, v4, s[6:7] offset:-3072
	s_sub_u32 s6, s6, 0x1000
	s_subb_u32 s7, s7, 0
	global_load_dword v18, v4, s[6:7]
	global_load_dword v19, v4, s[6:7] offset:-1024
	global_load_dword v20, v4, s[6:7] offset:-2048
	global_load_dword v21, v4, s[6:7] offset:-3072
	s_sub_u32 s6, s6, 0x1000
	s_subb_u32 s7, s7, 0
	global_load_dword v22, v4, s[6:7]
	global_load_dword v23, v4, s[6:7] offset:-1024
	global_load_dword v24, v4, s[6:7] offset:-2048
	global_load_dword v25, v4, s[6:7] offset:-3072
	s_sub_u32 s6, s6, 0x1000
	s_subb_u32 s7, s7, 0
	global_load_dword v26, v4, s[6:7]
	global_load_dword v27, v4, s[6:7] offset:-1024
	global_load_dword v28, v4, s[6:7] offset:-2048
	global_load_dword v29, v4, s[6:7] offset:-3072
	s_sub_u32 s6, s6, 0x1000
	s_subb_u32 s7, s7, 0
	global_load_dword v30, v4, s[6:7]
	global_load_dword v31, v4, s[6:7] offset:-1024
	global_load_dword v32, v4, s[6:7] offset:-2048
	global_load_dword v33, v4, s[6:7] offset:-3072
	s_sub_u32 s6, s6, 0x1000
	s_subb_u32 s7, s7, 0
	global_load_dword v34, v4, s[6:7]
	global_load_dword v35, v4, s[6:7] offset:-1024
	global_load_dword v36, v4, s[6:7] offset:-2048
	global_load_dword v37, v4, s[6:7] offset:-3072
	s_waitcnt vmcnt(31)
	v_cvt_pk_bf16_f32 v6, v6, v6
	ds_write_b16 v0, v6
	v_cmp_lt_i32_e32 vcc, 0, v1
	s_and_saveexec_b64 s[8:9], vcc
	ds_write_b16 v0, v6 offset:16446
	s_or_b64 exec, exec, s[8:9]
	s_waitcnt vmcnt(30)
	v_cvt_pk_bf16_f32 v7, v7, v7
	ds_write_b16 v0, v7 offset:512
	ds_write_b16 v0, v7 offset:16958
	s_waitcnt vmcnt(29)
	v_cvt_pk_bf16_f32 v8, v8, v8
	ds_write_b16 v0, v8 offset:1024
	ds_write_b16 v0, v8 offset:17470
	s_waitcnt vmcnt(28)
	v_cvt_pk_bf16_f32 v9, v9, v9
	ds_write_b16 v0, v9 offset:1536
	ds_write_b16 v0, v9 offset:17982
	s_waitcnt vmcnt(27)
	v_cvt_pk_bf16_f32 v10, v10, v10
	ds_write_b16 v0, v10 offset:2048
	ds_write_b16 v0, v10 offset:18494
	s_waitcnt vmcnt(26)
	v_cvt_pk_bf16_f32 v11, v11, v11
	ds_write_b16 v0, v11 offset:2560
	ds_write_b16 v0, v11 offset:19006
	s_waitcnt vmcnt(25)
	v_cvt_pk_bf16_f32 v12, v12, v12
	ds_write_b16 v0, v12 offset:3072
	ds_write_b16 v0, v12 offset:19518
	s_waitcnt vmcnt(24)
	v_cvt_pk_bf16_f32 v13, v13, v13
	ds_write_b16 v0, v13 offset:3584
	ds_write_b16 v0, v13 offset:20030
	s_waitcnt vmcnt(23)
	v_cvt_pk_bf16_f32 v14, v14, v14
	ds_write_b16 v0, v14 offset:4096
	ds_write_b16 v0, v14 offset:20542
	s_waitcnt vmcnt(22)
	v_cvt_pk_bf16_f32 v15, v15, v15
	ds_write_b16 v0, v15 offset:4608
	ds_write_b16 v0, v15 offset:21054
	s_waitcnt vmcnt(21)
	v_cvt_pk_bf16_f32 v16, v16, v16
	ds_write_b16 v0, v16 offset:5120
	ds_write_b16 v0, v16 offset:21566
	s_waitcnt vmcnt(20)
	v_cvt_pk_bf16_f32 v17, v17, v17
	ds_write_b16 v0, v17 offset:5632
	ds_write_b16 v0, v17 offset:22078
	s_waitcnt vmcnt(19)
	v_cvt_pk_bf16_f32 v18, v18, v18
	ds_write_b16 v0, v18 offset:6144
	ds_write_b16 v0, v18 offset:22590
	s_waitcnt vmcnt(18)
	v_cvt_pk_bf16_f32 v19, v19, v19
	ds_write_b16 v0, v19 offset:6656
	ds_write_b16 v0, v19 offset:23102
	s_waitcnt vmcnt(17)
	v_cvt_pk_bf16_f32 v20, v20, v20
	ds_write_b16 v0, v20 offset:7168
	ds_write_b16 v0, v20 offset:23614
	s_waitcnt vmcnt(16)
	v_cvt_pk_bf16_f32 v21, v21, v21
	ds_write_b16 v0, v21 offset:7680
	ds_write_b16 v0, v21 offset:24126
	s_waitcnt vmcnt(15)
	v_cvt_pk_bf16_f32 v22, v22, v22
	ds_write_b16 v0, v22 offset:8192
	ds_write_b16 v0, v22 offset:24638
	s_waitcnt vmcnt(14)
	v_cvt_pk_bf16_f32 v23, v23, v23
	ds_write_b16 v0, v23 offset:8704
	ds_write_b16 v0, v23 offset:25150
	s_waitcnt vmcnt(13)
	v_cvt_pk_bf16_f32 v24, v24, v24
	ds_write_b16 v0, v24 offset:9216
	ds_write_b16 v0, v24 offset:25662
	s_waitcnt vmcnt(12)
	v_cvt_pk_bf16_f32 v25, v25, v25
	ds_write_b16 v0, v25 offset:9728
	ds_write_b16 v0, v25 offset:26174
	s_waitcnt vmcnt(11)
	v_cvt_pk_bf16_f32 v26, v26, v26
	ds_write_b16 v0, v26 offset:10240
	ds_write_b16 v0, v26 offset:26686
	s_waitcnt vmcnt(10)
	v_cvt_pk_bf16_f32 v27, v27, v27
	ds_write_b16 v0, v27 offset:10752
	ds_write_b16 v0, v27 offset:27198
	s_waitcnt vmcnt(9)
	v_cvt_pk_bf16_f32 v28, v28, v28
	ds_write_b16 v0, v28 offset:11264
	ds_write_b16 v0, v28 offset:27710
	s_waitcnt vmcnt(8)
	v_cvt_pk_bf16_f32 v29, v29, v29
	ds_write_b16 v0, v29 offset:11776
	ds_write_b16 v0, v29 offset:28222
	s_waitcnt vmcnt(7)
	v_cvt_pk_bf16_f32 v30, v30, v30
	ds_write_b16 v0, v30 offset:12288
	ds_write_b16 v0, v30 offset:28734
	s_waitcnt vmcnt(6)
	v_cvt_pk_bf16_f32 v31, v31, v31
	ds_write_b16 v0, v31 offset:12800
	ds_write_b16 v0, v31 offset:29246
	s_waitcnt vmcnt(5)
	v_cvt_pk_bf16_f32 v32, v32, v32
	ds_write_b16 v0, v32 offset:13312
	ds_write_b16 v0, v32 offset:29758
	s_waitcnt vmcnt(4)
	v_cvt_pk_bf16_f32 v33, v33, v33
	ds_write_b16 v0, v33 offset:13824
	ds_write_b16 v0, v33 offset:30270
	s_waitcnt vmcnt(3)
	v_cvt_pk_bf16_f32 v34, v34, v34
	ds_write_b16 v0, v34 offset:14336
	ds_write_b16 v0, v34 offset:30782
	s_waitcnt vmcnt(2)
	v_cvt_pk_bf16_f32 v35, v35, v35
	ds_write_b16 v0, v35 offset:14848
	ds_write_b16 v0, v35 offset:31294
	s_waitcnt vmcnt(1)
	v_cvt_pk_bf16_f32 v36, v36, v36
	ds_write_b16 v0, v36 offset:15360
	ds_write_b16 v0, v36 offset:31806
	s_waitcnt vmcnt(0)
	v_cvt_pk_bf16_f32 v37, v37, v37
	ds_write_b16 v0, v37 offset:15872
	ds_write_b16 v0, v37 offset:32318

.LBB0_490:
	s_and_b64 vcc, exec, s[2:3]
	s_cbranch_vccz .LBB0_462
	s_nop 0
	v_mbcnt_lo_u32_b32 v0, -1, 0
	v_mbcnt_hi_u32_b32 v0, -1, v0
	s_ashr_i32 s4, s13, 1
	v_add_u32_e32 v10, s95, v0
	s_movk_i32 s0, 0x200
	s_ashr_i32 s5, s4, 31
	v_cmp_gt_i32_e32 vcc, s0, v10
	s_waitcnt lgkmcnt(0)
	s_barrier
	s_and_saveexec_b64 s[2:3], vcc
	s_cbranch_execz .LBB0_496
	v_readlane_b32 s20, v245, 51
	s_lshl_b64 s[0:1], s[4:5], 11
	v_readlane_b32 s24, v245, 55
	v_readlane_b32 s25, v245, 56
	s_add_u32 s6, s24, s0
	s_addc_u32 s7, s25, s1
	v_lshl_add_u32 v0, v10, 2, s52
	s_mov_b64 s[8:9], 0
	v_mov_b32_e32 v176, v10
	v_readlane_b32 s21, v245, 52
	v_readlane_b32 s22, v245, 53
	v_readlane_b32 s23, v245, 54
	v_readlane_b32 s26, v245, 57
	v_readlane_b32 s27, v245, 58
	s_branch .LBB0_494

.LBB0_504:
	s_or_b64 exec, exec, s[2:3]
	v_lshlrev_b32_e32 v0, 3, v10
	v_and_b32_e32 v9, 0xf8, v0
	v_lshl_add_u32 v8, v9, 2, s52
	s_waitcnt lgkmcnt(0)
	s_barrier
	ds_read_b128 v[0:3], v8 offset:1024
	s_nop 0
	ds_read_b128 v[4:7], v8 offset:1040
	v_ashrrev_i32_e32 v24, 5, v10
	v_mul_lo_u32 v11, v24, s10
	v_readlane_b32 s1, v246, 45
	v_and_b32_e32 v10, 31, v10
	v_mov_b32_e32 v12, 0
	v_add_u32_e32 v26, s1, v11
	v_readlane_b32 s1, v246, 46
	v_add_u32_e32 v25, 0x400, v8
	s_movk_i32 s3, 0x404
	v_lshl_add_u32 v27, v10, 5, s1
	s_mov_b32 s1, 0
	v_mov_b32_e32 v13, v12
	v_mov_b32_e32 v14, v12
	v_mov_b32_e32 v15, v12
	v_mov_b32_e32 v16, v12
	v_mov_b32_e32 v17, v12
	v_mov_b32_e32 v18, v12
	v_mov_b32_e32 v19, v12

.LBB0_512:
	s_nop 0
	v_mbcnt_lo_u32_b32 v0, -1, 0
	v_mbcnt_hi_u32_b32 v0, -1, v0
	s_lshl_b32 s0, s10, 8
	v_add_u32_e32 v32, s95, v0
	s_and_b32 s0, s0, 0x300
	v_lshlrev_b32_e32 v0, 3, v32
	v_and_b32_e32 v0, 0xf8, v0
	v_or_b32_e32 v33, s0, v0
	v_lshlrev_b32_e32 v176, 2, v33
	v_lshl_add_u64 v[8:9], s[4:5], 0, v[176:177]
	s_mov_b64 s[0:1], 0x1000
	v_lshl_add_u64 v[16:17], v[8:9], 0, s[0:1]
	s_mov_b64 s[0:1], 0x2000
	v_lshl_add_u64 v[20:21], v[8:9], 0, s[0:1]
	s_movk_i32 s0, 0x2000
	s_nop 0
	v_add_co_u32_e32 v12, vcc, s0, v8
	global_load_dwordx4 v[0:3], v176, s[4:5] offset:16
	global_load_dwordx4 v[4:7], v176, s[4:5]
	v_addc_co_u32_e32 v13, vcc, 0, v9, vcc
	global_load_dwordx4 v[8:11], v[12:13], off offset:-4096
	s_nop 0
	global_load_dwordx4 v[12:15], v[12:13], off
	s_nop 0
	global_load_dwordx4 v[16:19], v[16:17], off offset:16
	s_nop 0
	global_load_dwordx4 v[20:23], v[20:21], off offset:16
	s_nop 0
	global_load_dwordx4 v[24:27], v176, s[6:7] offset:16
	global_load_dwordx4 v[28:31], v176, s[6:7]
	s_ashr_i32 s0, s10, 2
	s_lshl_b32 s1, s0, 8
	s_lshl_b32 s8, s0, 6
	s_add_i32 s9, s1, 0xfffd0000
	s_cmpk_lt_i32 s0, 0x400
	s_cselect_b64 s[2:3], -1, 0
	s_and_b64 s[0:1], s[2:3], exec
	s_cselect_b32 s0, s8, s9
	s_cselect_b32 s8, 3, 5
	s_ashr_i32 s1, s0, 31
	v_ashrrev_i32_e32 v40, 5, v32
	s_lshl_b64 s[0:1], s[0:1], 11
	v_readlane_b32 s12, v248, 24
	v_mov_b32_e32 v32, v177
	v_readlane_b32 s13, v248, 25
	s_add_u32 s0, s12, s0
	s_addc_u32 s1, s13, s1
	v_mov_b64_e32 v[38:39], v[34:35]
	v_lshlrev_b32_e32 v176, 1, v33
	v_lshlrev_b32_e32 v70, s8, v40
	v_mov_b64_e32 v[36:37], v[32:33]
	v_lshl_add_u64 v[68:69], s[0:1], 0, v[176:177]
	v_cmp_lt_i32_e32 vcc, 0, v40
	v_ashrrev_i32_e32 v71, 31, v70
	v_mov_b32_e32 v37, v32
	v_mov_b32_e32 v38, v32
	v_mov_b32_e32 v39, v32
	s_and_saveexec_b64 s[8:9], vcc
	s_cbranch_execz .LBB0_514
	v_lshlrev_b64 v[34:35], 11, v[70:71]
	v_lshl_add_u64 v[34:35], v[68:69], 0, v[34:35]
	global_load_dwordx4 v[36:39], v[34:35], off offset:-2048

.LBB0_538:
	s_mul_hi_i32 s1, s0, 0x55555556
	s_lshr_b32 s2, s1, 31
	s_add_i32 s1, s1, s2
	s_mul_i32 s2, s1, -3
	s_add_i32 s2, s2, s0
	s_nop 0
	v_mbcnt_lo_u32_b32 v0, -1, 0
	v_mbcnt_hi_u32_b32 v0, -1, v0
	s_lshl_b32 s8, s2, 8
	v_add_u32_e32 v9, s95, v0
	s_movk_i32 s2, 0x840
	s_lshl_b32 s10, s1, 6
	v_cmp_gt_i32_e32 vcc, s2, v9
	s_waitcnt lgkmcnt(0)
	s_barrier
	s_and_saveexec_b64 s[2:3], vcc
	s_cbranch_execz .LBB0_545
	s_cmpk_gt_i32 s0, 0xbff
	s_cselect_b64 s[14:15], -1, 0
	s_and_b32 s1, s1, 3
	s_cmp_lg_u32 s1, 0
	s_cselect_b64 s[16:17], -1, 0
	s_cmp_lg_u32 s1, 3
	s_cselect_b64 s[12:13], -1, 0
	s_ashr_i32 s9, s8, 31
	v_readlane_b32 s36, v246, 63
	s_and_b64 s[12:13], s[14:15], s[12:13]
	s_and_b64 s[14:15], s[14:15], s[16:17]
	s_lshl_b64 s[16:17], s[8:9], 1
	v_readlane_b32 s48, v245, 11
	v_readlane_b32 s49, v245, 12
	s_add_u32 s16, s48, s16
	v_lshlrev_b32_e32 v0, 4, v9
	s_addc_u32 s17, s49, s17
	v_and_b32_e32 v176, 0x1f0, v0
	s_add_i32 s1, s10, -1
	s_nop 0
	v_lshl_add_u64 v[6:7], s[16:17], 0, v[176:177]
	v_add_u32_e32 v8, s52, v176
	s_mov_b64 s[16:17], 0
	v_mov_b32_e32 v5, v9
	v_readlane_b32 s37, v245, 0
	v_readlane_b32 s38, v245, 1
	v_readlane_b32 s39, v245, 2
	v_readlane_b32 s40, v245, 3
	v_readlane_b32 s41, v245, 4
	v_readlane_b32 s42, v245, 5
	v_readlane_b32 s43, v245, 6
	v_readlane_b32 s44, v245, 7
	v_readlane_b32 s45, v245, 8
	v_readlane_b32 s46, v245, 9
	v_readlane_b32 s47, v245, 10
	v_readlane_b32 s50, v245, 13
	v_readlane_b32 s51, v245, 14
	v_ashrrev_i32_e32 v10, 5, v9
	v_add_u32_e32 v0, s1, v10
	s_movk_i32 s5, 0x600
	v_mad_i64_i32 v[12:13], s[20:21], v0, s5, v[6:7]
	s_movk_i32 s5, 0x210
	v_mad_u64_u32 v[14:15], s[20:21], v10, s5, v[8:9]
	s_mov_b64 s[22:23], 0x3000
	v_mov_b32_e32 v16, 0
	v_mov_b32_e32 v17, 0
	v_mov_b32_e32 v18, 0
	v_mov_b32_e32 v19, 0
	v_mov_b32_e32 v48, 0
	v_mov_b32_e32 v49, 0
	v_mov_b32_e32 v50, 0
	v_mov_b32_e32 v51, 0
	v_cmp_lt_u32_e32 vcc, 31, v9
	s_or_b64 s[20:21], vcc, s[14:15]
	s_and_saveexec_b64 s[28:29], s[20:21]
	global_load_dwordx4 v[16:19], v[12:13], off
	s_mov_b64 exec, s[28:29]
	v_lshl_add_u64 v[12:13], v[12:13], 0, s[22:23]
	global_load_dwordx4 v[20:23], v[12:13], off
	v_lshl_add_u64 v[12:13], v[12:13], 0, s[22:23]
	global_load_dwordx4 v[24:27], v[12:13], off
	v_lshl_add_u64 v[12:13], v[12:13], 0, s[22:23]
	global_load_dwordx4 v[28:31], v[12:13], off
	v_lshl_add_u64 v[12:13], v[12:13], 0, s[22:23]
	global_load_dwordx4 v[32:35], v[12:13], off
	v_lshl_add_u64 v[12:13], v[12:13], 0, s[22:23]
	global_load_dwordx4 v[36:39], v[12:13], off
	v_lshl_add_u64 v[12:13], v[12:13], 0, s[22:23]
	global_load_dwordx4 v[40:43], v[12:13], off
	v_lshl_add_u64 v[12:13], v[12:13], 0, s[22:23]
	global_load_dwordx4 v[44:47], v[12:13], off
	v_lshl_add_u64 v[12:13], v[12:13], 0, s[22:23]
	v_cmp_gt_u32_e32 vcc, 32, v9
	s_mov_b64 s[20:21], vcc
	v_cmp_gt_u32_e32 vcc, 64, v9
	s_and_b64 s[28:29], vcc, s[12:13]
	s_or_b64 s[20:21], s[20:21], s[28:29]
	s_and_saveexec_b64 s[28:29], s[20:21]
	global_load_dwordx4 v[48:51], v[12:13], off
	s_mov_b64 exec, s[28:29]
	s_waitcnt vmcnt(8)
	ds_write_b128 v14, v[16:19]
	s_waitcnt vmcnt(7)
	ds_write_b128 v14, v[20:23] offset:4224
	s_waitcnt vmcnt(6)
	ds_write_b128 v14, v[24:27] offset:8448
	s_waitcnt vmcnt(5)
	ds_write_b128 v14, v[28:31] offset:12672
	s_waitcnt vmcnt(4)
	ds_write_b128 v14, v[32:35] offset:16896
	s_waitcnt vmcnt(3)
	ds_write_b128 v14, v[36:39] offset:21120
	s_waitcnt vmcnt(2)
	ds_write_b128 v14, v[40:43] offset:25344
	s_waitcnt vmcnt(1)
	ds_write_b128 v14, v[44:47] offset:29568
	s_waitcnt vmcnt(0)
	v_cmp_gt_u32_e32 vcc, 64, v9
	s_and_saveexec_b64 s[28:29], vcc
	ds_write_b128 v14, v[48:51] offset:33792
	s_mov_b64 exec, s[28:29]
